# MLA: softmax scale folded into the q projection rstd, QK accumulators start at -m (srcC block) so exp2 applies directly; B fragments reuse A registers; K prefetch
# speedup vs baseline: 1.0538x; 1.0277x over previous
.LBB0_79:
	s_waitcnt lgkmcnt(0)
	global_load_dwordx4 v[10:13], v[4:5], off
	s_waitcnt vmcnt(0)
	v_add_f32_e32 v9, v10, v11
	v_add_f32_e32 v10, v12, v13
	v_add_f32_e32 v9, v9, v10
	v_cndmask_b32_e64 v10, 0, v9, s[36:37]
	v_cndmask_b32_e64 v9, 0, v9, s[38:39]
	ds_bpermute_b32 v11, v6, v10
	ds_bpermute_b32 v12, v6, v9
	s_waitcnt lgkmcnt(1)
	v_add_f32_e32 v10, v10, v11
	s_waitcnt lgkmcnt(0)
	v_add_f32_e32 v9, v9, v12
	ds_bpermute_b32 v11, v7, v10
	ds_bpermute_b32 v12, v7, v9
	s_waitcnt lgkmcnt(1)
	v_add_f32_e32 v10, v10, v11
	s_waitcnt lgkmcnt(0)
	v_add_f32_e32 v9, v9, v12
	ds_bpermute_b32 v12, v8, v10
	ds_bpermute_b32 v11, v8, v9
	s_and_saveexec_b64 s[44:45], s[40:41]
	s_cbranch_execz .LBB0_78
	s_waitcnt lgkmcnt(1)
	v_add_f32_e32 v10, v10, v12
	v_fmamk_f32 v10, v10, 0x3b2aaaab, v185
	v_rsq_f32_e32 v10, v10
	s_waitcnt lgkmcnt(0)
	v_add_f32_e32 v9, v9, v11
	v_fmamk_f32 v9, v9, 0x3b800000, v185
	v_rsq_f32_e32 v9, v9
	v_mul_f32_e32 v10, 0x3e16c740, v10
	global_store_dword v[2:3], v10, off
	v_add_co_u32_e32 v10, vcc, 0x20000, v2
	s_nop 1
	v_addc_co_u32_e32 v11, vcc, 0, v3, vcc
	global_store_dword v[10:11], v9, off
	s_branch .LBB0_78

.LBB0_485:
	s_andn2_b64 vcc, exec, s[40:41]
	s_cbranch_vccnz .LBB0_498
	s_cmp_eq_u32 s30, 0
	s_cbranch_scc1 .Lmla_slow
	s_cmp_le_u32 s31, s4
	s_cbranch_scc1 .Lmla_fast
.Lmla_slow:
	v_add_f32_e32 v254, v202, v203
	v_add_f32_e32 v255, v204, v205
	v_add_f32_e32 v254, v254, v206
	v_add_f32_e32 v255, v255, v207
	v_add_f32_e32 v254, v254, v208
	v_add_f32_e32 v255, v255, v209
	v_add_f32_e32 v254, v254, v210
	v_add_f32_e32 v255, v255, v211
	v_add_f32_e32 v254, v254, v212
	v_add_f32_e32 v255, v255, v213
	v_add_f32_e32 v254, v254, v214
	v_add_f32_e32 v255, v255, v215
	v_add_f32_e32 v254, v254, v216
	v_add_f32_e32 v255, v255, v217
	v_add_f32_e32 v254, v254, v218
	v_add_f32_e32 v255, v255, v219
	v_add_f32_e32 v254, v254, v220
	v_add_f32_e32 v255, v255, v221
	v_add_f32_e32 v254, v254, v222
	v_add_f32_e32 v255, v255, v223
	v_add_f32_e32 v254, v254, v224
	v_add_f32_e32 v255, v255, v225
	v_add_f32_e32 v254, v254, v226
	v_add_f32_e32 v255, v255, v227
	v_add_f32_e32 v254, v254, v228
	v_add_f32_e32 v255, v255, v229
	v_add_f32_e32 v254, v254, v230
	v_add_f32_e32 v255, v255, v231
	v_add_f32_e32 v254, v254, v232
	v_add_f32_e32 v255, v255, v233
	v_add_f32_e32 v254, v254, v255
	v_add_f32_e32 v147, v147, v254
	v_mov_b64_e32 v[202:203], 0
	v_mov_b64_e32 v[204:205], 0
	v_mov_b64_e32 v[206:207], 0
	v_mov_b64_e32 v[208:209], 0
	v_mov_b64_e32 v[210:211], 0
	v_mov_b64_e32 v[212:213], 0
	v_mov_b64_e32 v[214:215], 0
	v_mov_b64_e32 v[216:217], 0
	v_mov_b64_e32 v[218:219], 0
	v_mov_b64_e32 v[220:221], 0
	v_mov_b64_e32 v[222:223], 0
	v_mov_b64_e32 v[224:225], 0
	v_mov_b64_e32 v[226:227], 0
	v_mov_b64_e32 v[228:229], 0
	v_mov_b64_e32 v[230:231], 0
	v_mov_b64_e32 v[232:233], 0
	s_and_b32 s8, s30, 3
	s_mulk_i32 s8, 0x6400
	s_add_i32 s8, s8, 0
	v_add3_u32 v0, s8, v143, v132
	ds_read_b128 v[34:37], v0
	ds_read_b128 v[150:153], v0 offset:32
	ds_read_b128 v[38:41], v0 offset:6656
	ds_read_b128 v[154:157], v0 offset:6688
	ds_read_b128 v[158:161], v0 offset:64
	ds_read_b128 v[162:165], v0 offset:96
	ds_read_b128 v[166:169], v0 offset:6720
	ds_read_b128 v[170:173], v0 offset:6752
	ds_read_b128 v[174:177], v0 offset:128
	ds_read_b128 v[178:181], v0 offset:160
	ds_read_b128 v[194:197], v0 offset:6784
	ds_read_b128 v[198:201], v0 offset:6816
	v_add3_u32 v0, s8, v144, v145
	ds_read_b64_tr_b16 v[126:127], v0 offset:13312
	ds_read_b64_tr_b16 v[128:129], v0 offset:14848
	ds_read_b64_tr_b16 v[124:125], v0 offset:14912
	ds_read_b64_tr_b16 v[122:123], v0 offset:13376
	ds_read_b64_tr_b16 v[118:119], v0 offset:16384
	ds_read_b64_tr_b16 v[120:121], v0 offset:17920
	ds_read_b64_tr_b16 v[116:117], v0 offset:17984
	ds_read_b64_tr_b16 v[114:115], v0 offset:16448
	ds_read_b64_tr_b16 v[110:111], v0 offset:19456
	ds_read_b64_tr_b16 v[112:113], v0 offset:20992
	ds_read_b64_tr_b16 v[108:109], v0 offset:21056
	ds_read_b64_tr_b16 v[106:107], v0 offset:19520
	ds_read_b64_tr_b16 v[102:103], v0 offset:22528
	ds_read_b64_tr_b16 v[104:105], v0 offset:24064
	ds_read_b64_tr_b16 v[100:101], v0 offset:24128
	ds_read_b64_tr_b16 v[98:99], v0 offset:22592
	s_waitcnt lgkmcnt(0)
	v_mfma_f32_32x32x16_bf16 v[50:65], v[34:37], v[74:77], 0
	v_mfma_f32_32x32x16_bf16 v[34:49], v[38:41], v[74:77], 0
	v_mfma_f32_32x32x16_bf16 v[50:65], v[150:153], v[78:81], v[50:65]
	v_mfma_f32_32x32x16_bf16 v[34:49], v[154:157], v[78:81], v[34:49]
	v_mfma_f32_32x32x16_bf16 v[50:65], v[158:161], v[82:85], v[50:65]
	v_mfma_f32_32x32x16_bf16 v[34:49], v[166:169], v[82:85], v[34:49]
	v_mfma_f32_32x32x16_bf16 v[50:65], v[162:165], v[86:89], v[50:65]
	v_mfma_f32_32x32x16_bf16 v[34:49], v[170:173], v[86:89], v[34:49]
	v_mfma_f32_32x32x16_bf16 v[50:65], v[174:177], v[90:93], v[50:65]
	v_mfma_f32_32x32x16_bf16 v[34:49], v[194:197], v[90:93], v[34:49]
	v_mfma_f32_32x32x16_bf16 v[50:65], v[178:181], v[94:97], v[50:65]
	v_mfma_f32_32x32x16_bf16 v[34:49], v[198:201], v[94:97], v[34:49]
	s_andn2_b64 vcc, exec, s[38:39]
	s_cbranch_vccnz .LBB0_493
	s_add_i32 s34, s30, 2
	s_cmp_gt_u32 s34, s14
	s_cbranch_scc1 .LBB0_490
	s_and_b32 s8, s34, 2
	s_mulk_i32 s8, 0x6400
	s_add_i32 s34, s8, 0
	s_add_i32 s8, s34, s5
	s_mov_b32 m0, s8
	s_and_b64 vcc, exec, s[36:37]
	global_load_lds_dwordx4 v[66:67], off
	s_add_i32 m0, s8, 0x2000
	v_lshl_add_u64 v[66:67], v[66:67], 0, v[134:135]
	global_load_lds_dwordx4 v[68:69], off
	s_add_i32 m0, s8, 0x4000
	v_lshl_add_u64 v[68:69], v[68:69], 0, v[136:137]
	global_load_lds_dwordx4 v[70:71], off
	v_lshl_add_u64 v[70:71], v[70:71], 0, v[138:139]
	s_cbranch_vccnz .LBB0_490
	s_add_i32 m0, s34, 0x6000
	v_lshl_add_u64 v[150:151], v[72:73], 0, v[140:141]
	global_load_lds_dwordx4 v[72:73], off
	v_mov_b32_e32 v72, v150
	v_mov_b32_e32 v73, v151

.LBB0_495:
	s_nop 15
	s_nop 3
	s_nop 0
	v_max3_f32 v0, v50, v51, v52
	v_max3_f32 v0, v0, v53, v54
	v_max3_f32 v0, v0, v55, v56
	v_max3_f32 v0, v0, v57, v58
	v_max3_f32 v0, v0, v59, v60
	v_max3_f32 v0, v0, v61, v62
	v_max3_f32 v0, v0, v63, v64
	v_max3_f32 v0, v0, v65, v65
	v_max3_f32 v149, v34, v35, v36
	v_max3_f32 v149, v149, v37, v38
	v_max3_f32 v149, v149, v39, v40
	v_max3_f32 v149, v149, v41, v42
	v_max3_f32 v149, v149, v43, v44
	v_max3_f32 v149, v149, v45, v46
	v_max3_f32 v149, v149, v47, v48
	v_max3_f32 v149, v149, v49, v49
	s_nop 0
	v_max_f32_e32 v149, v149, v149
	v_max_f32_e32 v0, v0, v0
	v_max_f32_e32 v0, v0, v149
	v_sub_f32_e32 v149, v0, v148
	v_mul_f32_e32 v149, 1.0, v149
	v_cmp_lt_f32_e32 vcc, s21, v149
	s_cbranch_vccz .LBB0_497
	v_xor_b32_e32 v149, 32, v187
	v_cmp_lt_i32_e32 vcc, v149, v189
	s_nop 1
	v_cndmask_b32_e32 v149, v187, v149, vcc
	v_lshlrev_b32_e32 v149, 2, v149
	ds_bpermute_b32 v149, v149, v0
	s_waitcnt lgkmcnt(0)
	v_max3_f32 v149, v148, v0, v149
	v_sub_f32_e32 v0, v148, v149
	v_mul_f32_e32 v0, 0x3f800000, v0
	v_exp_f32_e32 v0, v0
	v_mov_b32_e32 v148, v149
	v_pk_mul_f32 v[32:33], v[32:33], v[0:1] op_sel_hi:[1,0]
	v_pk_mul_f32 v[30:31], v[30:31], v[0:1] op_sel_hi:[1,0]
	v_pk_mul_f32 v[28:29], v[28:29], v[0:1] op_sel_hi:[1,0]
	v_pk_mul_f32 v[26:27], v[26:27], v[0:1] op_sel_hi:[1,0]
	v_pk_mul_f32 v[24:25], v[24:25], v[0:1] op_sel_hi:[1,0]
	v_pk_mul_f32 v[22:23], v[22:23], v[0:1] op_sel_hi:[1,0]
	v_pk_mul_f32 v[20:21], v[20:21], v[0:1] op_sel_hi:[1,0]
	v_pk_mul_f32 v[18:19], v[18:19], v[0:1] op_sel_hi:[1,0]
	v_pk_mul_f32 v[16:17], v[16:17], v[0:1] op_sel_hi:[1,0]
	v_pk_mul_f32 v[14:15], v[14:15], v[0:1] op_sel_hi:[1,0]
	v_pk_mul_f32 v[12:13], v[12:13], v[0:1] op_sel_hi:[1,0]
	v_pk_mul_f32 v[10:11], v[10:11], v[0:1] op_sel_hi:[1,0]
	v_pk_mul_f32 v[8:9], v[8:9], v[0:1] op_sel_hi:[1,0]
	v_pk_mul_f32 v[6:7], v[6:7], v[0:1] op_sel_hi:[1,0]
	v_pk_mul_f32 v[4:5], v[4:5], v[0:1] op_sel_hi:[1,0]
	v_pk_mul_f32 v[2:3], v[2:3], v[0:1] op_sel_hi:[1,0]
	v_mul_f32_e32 v147, v147, v0
	v_mul_f32_e32 v234, -1.0, v148
	v_mul_f32_e32 v235, -1.0, v148
	v_mul_f32_e32 v236, -1.0, v148
	v_mul_f32_e32 v237, -1.0, v148
	v_mul_f32_e32 v238, -1.0, v148
	v_mul_f32_e32 v239, -1.0, v148
	v_mul_f32_e32 v240, -1.0, v148
	v_mul_f32_e32 v241, -1.0, v148
	v_mul_f32_e32 v242, -1.0, v148
	v_mul_f32_e32 v243, -1.0, v148
	v_mul_f32_e32 v244, -1.0, v148
	v_mul_f32_e32 v245, -1.0, v148
	v_mul_f32_e32 v246, -1.0, v148
	v_mul_f32_e32 v247, -1.0, v148
	v_mul_f32_e32 v248, -1.0, v148
	v_mul_f32_e32 v249, -1.0, v148
.LBB0_497:
	v_mul_f32_e32 v0, -1.0, v148
	v_fmamk_f32 v36, v36, 0x3f800000, v0
	v_exp_f32_e32 v152, v36
	v_fmamk_f32 v36, v53, 0x3f800000, v0
	v_exp_f32_e32 v156, v36
	v_fmamk_f32 v36, v37, 0x3f800000, v0
	v_fmamk_f32 v34, v34, 0x3f800000, v0
	v_exp_f32_e32 v157, v36
	v_fmamk_f32 v36, v54, 0x3f800000, v0
	v_exp_f32_e32 v150, v34
	v_fmamk_f32 v34, v51, 0x3f800000, v0
	v_exp_f32_e32 v51, v36
	v_fmamk_f32 v36, v38, 0x3f800000, v0
	v_fmamk_f32 v50, v50, 0x3f800000, v0
	v_exp_f32_e32 v53, v36
	v_fmamk_f32 v36, v55, 0x3f800000, v0
	v_exp_f32_e32 v149, v50
	v_fmamk_f32 v35, v35, 0x3f800000, v0
	v_exp_f32_e32 v50, v36
	v_fmamk_f32 v36, v39, 0x3f800000, v0
	v_exp_f32_e32 v151, v35
	v_fmamk_f32 v35, v52, 0x3f800000, v0
	v_exp_f32_e32 v52, v36
	v_fmamk_f32 v36, v56, 0x3f800000, v0
	v_exp_f32_e32 v39, v36
	v_fmamk_f32 v36, v57, 0x3f800000, v0
	v_exp_f32_e32 v34, v34
	v_exp_f32_e32 v35, v35
	v_exp_f32_e32 v38, v36
	v_fmamk_f32 v36, v58, 0x3f800000, v0
	v_exp_f32_e32 v55, v36
	v_fmamk_f32 v36, v60, 0x3f800000, v0
	v_add_f32_e32 v154, v34, v151
	v_add_f32_e32 v155, v35, v152
	v_exp_f32_e32 v57, v36
	v_cvt_pk_bf16_f32 v37, v39, v38
	v_cvt_pk_bf16_f32 v36, v51, v50
	v_cvt_pk_bf16_f32 v35, v35, v156
	v_cvt_pk_bf16_f32 v34, v149, v34
	v_fmamk_f32 v58, v62, 0x3f800000, v0
	v_fmamk_f32 v60, v64, 0x3f800000, v0
	v_mfma_f32_32x32x16_bf16 v[18:33], v[126:129], v[34:37], v[18:33]
	v_fmamk_f32 v54, v59, 0x3f800000, v0
	v_fmamk_f32 v56, v61, 0x3f800000, v0
	v_exp_f32_e32 v59, v58
	v_fmamk_f32 v58, v63, 0x3f800000, v0
	v_exp_f32_e32 v61, v60
	v_fmamk_f32 v60, v65, 0x3f800000, v0
	v_exp_f32_e32 v60, v60
	v_mfma_f32_32x32x16_bf16 v[2:17], v[122:125], v[34:37], v[2:17]
	v_exp_f32_e32 v58, v58
	v_exp_f32_e32 v56, v56
	v_exp_f32_e32 v54, v54
	v_cvt_pk_bf16_f32 v37, v61, v60
	v_cvt_pk_bf16_f32 v36, v59, v58
	v_cvt_pk_bf16_f32 v35, v57, v56
	v_cvt_pk_bf16_f32 v34, v55, v54
	v_fmamk_f32 v40, v40, 0x3f800000, v0
	v_exp_f32_e32 v63, v40
	v_mfma_f32_32x32x16_bf16 v[18:33], v[118:121], v[34:37], v[18:33]
	v_fmamk_f32 v40, v41, 0x3f800000, v0
	v_exp_f32_e32 v62, v40
	v_fmamk_f32 v40, v42, 0x3f800000, v0
	v_exp_f32_e32 v41, v40
	v_fmamk_f32 v40, v43, 0x3f800000, v0
	v_fmamk_f32 v42, v45, 0x3f800000, v0
	v_exp_f32_e32 v42, v42
	v_mfma_f32_32x32x16_bf16 v[2:17], v[114:117], v[34:37], v[2:17]
	v_fmamk_f32 v34, v44, 0x3f800000, v0
	v_exp_f32_e32 v43, v34
	v_cvt_pk_bf16_f32 v37, v63, v62
	v_cvt_pk_bf16_f32 v36, v53, v52
	v_cvt_pk_bf16_f32 v35, v152, v157
	v_cvt_pk_bf16_f32 v34, v150, v151
	v_fmamk_f32 v44, v46, 0x3f800000, v0
	v_exp_f32_e32 v45, v44
	v_mfma_f32_32x32x16_bf16 v[18:33], v[110:113], v[34:37], v[18:33]
	v_fmamk_f32 v44, v47, 0x3f800000, v0
	v_fmamk_f32 v46, v48, 0x3f800000, v0
	v_fmac_f32_e32 v0, 1.0, v49
	v_exp_f32_e32 v47, v46
	v_exp_f32_e32 v46, v0
	v_exp_f32_e32 v44, v44
	v_exp_f32_e32 v40, v40
	v_mfma_f32_32x32x16_bf16 v[2:17], v[106:109], v[34:37], v[2:17]
	v_add_f32_e32 v153, v149, v150
	v_cvt_pk_bf16_f32 v37, v47, v46
	v_cvt_pk_bf16_f32 v36, v45, v44
	v_cvt_pk_bf16_f32 v35, v43, v42
	v_cvt_pk_bf16_f32 v34, v41, v40
	v_add_f32_e32 v0, v156, v157
	v_pk_add_f32 v[48:49], v[50:51], v[52:53]
	v_mfma_f32_32x32x16_bf16 v[18:33], v[102:105], v[34:37], v[18:33]
	v_add_f32_e64 v38, v38, v62
	v_add_f32_e64 v39, v39, v63
	v_add_f32_e64 v40, v54, v40
	v_add_f32_e64 v41, v55, v41
	v_add_f32_e64 v42, v56, v42
	v_add_f32_e64 v43, v57, v43
	v_pk_add_f32 v[44:45], v[58:59], v[44:45]
	v_pk_add_f32 v[46:47], v[60:61], v[46:47]
	v_mfma_f32_32x32x16_bf16 v[2:17], v[98:101], v[34:37], v[2:17]
	v_add_f32_e32 v34, 0, v153
	v_add_f32_e32 v34, v154, v34
	v_add_f32_e32 v34, v155, v34
	v_add_f32_e32 v0, v0, v34
	v_add_f32_e32 v0, v49, v0
	v_add_f32_e32 v0, v48, v0
	v_add_f32_e32 v0, v39, v0
	v_add_f32_e32 v0, v38, v0
	v_add_f32_e32 v0, v41, v0
	v_add_f32_e32 v0, v40, v0
	v_add_f32_e32 v0, v43, v0
	v_add_f32_e32 v0, v42, v0
	v_add_f32_e32 v0, v45, v0
	v_add_f32_e32 v0, v44, v0
	v_add_f32_e32 v0, v47, v0
	v_add_f32_e32 v0, v46, v0
	v_add_f32_e32 v147, v147, v0

.Lmla_fast:
	s_and_b32 s8, s30, 3
	s_mulk_i32 s8, 0x6400
	s_add_i32 s8, s8, 0
	v_add3_u32 v142, s8, v144, v145
	v_add3_u32 v0, s8, v143, v132
	s_cmp_lg_u32 s42, 0
	s_cbranch_scc1 .Lmla_fast_havek
	ds_read_b128 v[194:197], v0
	ds_read_b128 v[150:153], v0 offset:32
	ds_read_b128 v[158:161], v0 offset:64
	ds_read_b128 v[162:165], v0 offset:96
	ds_read_b128 v[174:177], v0 offset:128
	ds_read_b128 v[178:181], v0 offset:160

.Lmla_fast_nodma:
	s_waitcnt lgkmcnt(0)
	v_mfma_f32_32x32x16_bf16 v[50:65], v[194:197], v[74:77], v[234:249]
	ds_read_b128 v[194:197], v0 offset:6656
	v_add_f32_e32 v254, v202, v203
	v_add_f32_e32 v255, v204, v205
	v_add_f32_e32 v254, v254, v206
	v_add_f32_e32 v255, v255, v207
	v_add_f32_e32 v254, v254, v208
	v_add_f32_e32 v255, v255, v209
	v_mfma_f32_32x32x16_bf16 v[50:65], v[150:153], v[78:81], v[50:65]
	ds_read_b128 v[150:153], v0 offset:6688
	v_add_f32_e32 v254, v254, v210
	v_add_f32_e32 v255, v255, v211
	v_add_f32_e32 v254, v254, v212
	v_add_f32_e32 v255, v255, v213
	v_add_f32_e32 v254, v254, v214
	v_add_f32_e32 v255, v255, v215
	v_mfma_f32_32x32x16_bf16 v[50:65], v[158:161], v[82:85], v[50:65]
	ds_read_b128 v[158:161], v0 offset:6720
	v_add_f32_e32 v254, v254, v216
	v_add_f32_e32 v255, v255, v217
	v_add_f32_e32 v254, v254, v218
	v_add_f32_e32 v255, v255, v219
	v_add_f32_e32 v254, v254, v220
	v_mfma_f32_32x32x16_bf16 v[50:65], v[162:165], v[86:89], v[50:65]
	ds_read_b128 v[162:165], v0 offset:6752
	v_add_f32_e32 v255, v255, v221
	v_add_f32_e32 v254, v254, v222
	v_add_f32_e32 v255, v255, v223
	v_add_f32_e32 v254, v254, v224
	v_add_f32_e32 v255, v255, v225
	v_mfma_f32_32x32x16_bf16 v[50:65], v[174:177], v[90:93], v[50:65]
	ds_read_b128 v[174:177], v0 offset:6784
	v_add_f32_e32 v254, v254, v226
	v_add_f32_e32 v255, v255, v227
	v_add_f32_e32 v254, v254, v228
	v_add_f32_e32 v255, v255, v229
	v_add_f32_e32 v254, v254, v230
	v_mfma_f32_32x32x16_bf16 v[50:65], v[178:181], v[94:97], v[50:65]
	ds_read_b128 v[178:181], v0 offset:6816
	v_add_f32_e32 v255, v255, v231
	v_add_f32_e32 v254, v254, v232
	v_add_f32_e32 v255, v255, v233
	v_add_f32_e32 v254, v254, v255
	v_add_f32_e32 v147, v147, v254
	s_waitcnt lgkmcnt(5)
	v_mfma_f32_32x32x16_bf16 v[34:49], v[194:197], v[74:77], v[234:249]
	ds_read_b64_tr_b16 v[126:127], v142 offset:13312
	ds_read_b64_tr_b16 v[128:129], v142 offset:14848
	ds_read_b64_tr_b16 v[124:125], v142 offset:14912
	ds_read_b64_tr_b16 v[122:123], v142 offset:13376
	ds_read_b64_tr_b16 v[118:119], v142 offset:16384
	ds_read_b64_tr_b16 v[120:121], v142 offset:17920
	s_waitcnt lgkmcnt(10)
	v_mfma_f32_32x32x16_bf16 v[34:49], v[150:153], v[78:81], v[34:49]
	ds_read_b64_tr_b16 v[116:117], v142 offset:17984
	ds_read_b64_tr_b16 v[114:115], v142 offset:16448
	ds_read_b64_tr_b16 v[110:111], v142 offset:19456
	ds_read_b64_tr_b16 v[112:113], v142 offset:20992
	ds_read_b64_tr_b16 v[108:109], v142 offset:21056
	ds_read_b64_tr_b16 v[106:107], v142 offset:19520
	s_waitcnt lgkmcnt(15)
	v_mfma_f32_32x32x16_bf16 v[34:49], v[158:161], v[82:85], v[34:49]
	ds_read_b64_tr_b16 v[102:103], v142 offset:22528
	ds_read_b64_tr_b16 v[104:105], v142 offset:24064
	ds_read_b64_tr_b16 v[100:101], v142 offset:24128
	ds_read_b64_tr_b16 v[98:99], v142 offset:22592
	v_max3_f32 v0, v50, v51, v52
	v_max3_f32 v0, v0, v53, v54
	s_waitcnt lgkmcnt(15)
	v_mfma_f32_32x32x16_bf16 v[34:49], v[162:165], v[86:89], v[34:49]
	v_max3_f32 v0, v0, v55, v56
	v_max3_f32 v0, v0, v57, v58
	v_max3_f32 v0, v0, v59, v60
	v_max3_f32 v0, v0, v61, v62
	v_max3_f32 v0, v0, v63, v64
	v_max3_f32 v0, v0, v65, v65
	v_mfma_f32_32x32x16_bf16 v[34:49], v[174:177], v[90:93], v[34:49]
	v_exp_f32_e32 v202, v50
	v_exp_f32_e32 v203, v51
	v_exp_f32_e32 v204, v52
	v_mfma_f32_32x32x16_bf16 v[34:49], v[178:181], v[94:97], v[34:49]
	s_and_b64 vcc, exec, s[16:17]
	s_cbranch_vccz .Lmla_fast_nostag
	s_waitcnt vmcnt(0) lgkmcnt(0)
	s_barrier
	s_mov_b64 s[16:17], 0
.Lmla_fast_nostag:
	v_exp_f32_e32 v205, v53
	v_exp_f32_e32 v206, v54
	v_exp_f32_e32 v207, v55
	v_exp_f32_e32 v208, v56
	v_exp_f32_e32 v209, v57
	v_exp_f32_e32 v210, v58
	v_exp_f32_e32 v211, v59
	v_exp_f32_e32 v212, v60
	v_exp_f32_e32 v213, v61
	v_exp_f32_e32 v214, v62
	v_max3_f32 v149, v34, v35, v36
	v_exp_f32_e32 v215, v63
	v_max3_f32 v149, v149, v37, v38
	v_exp_f32_e32 v216, v64
	v_max3_f32 v149, v149, v39, v40
	v_exp_f32_e32 v217, v65
	v_max3_f32 v149, v149, v41, v42
	v_max3_f32 v149, v149, v43, v44
	v_max3_f32 v149, v149, v45, v46
	v_max3_f32 v149, v149, v47, v48
	v_max3_f32 v149, v149, v49, v49
	v_max_f32_e32 v149, v149, v149
	v_max_f32_e32 v0, v0, v0
	v_max_f32_e32 v0, v0, v149
	v_cmp_lt_f32_e32 vcc, s21, v0
	s_cbranch_vccnz .Lmla_fast_rescale
.Lmla_fast_ok:
	v_cvt_pk_bf16_f32 v166, v202, v203
	v_cvt_pk_bf16_f32 v167, v204, v205
	v_cvt_pk_bf16_f32 v168, v206, v207
	v_cvt_pk_bf16_f32 v169, v208, v209
	s_waitcnt lgkmcnt(0)
	s_add_i32 s34, s31, 64
	s_cmp_le_u32 s34, s4
	s_cselect_b32 s42, 1, 0
	s_add_i32 s8, s30, 1
	s_and_b32 s8, s8, 3
	s_mulk_i32 s8, 0x6400
	v_add3_u32 v0, s8, v143, v132
	v_mfma_f32_32x32x16_bf16 v[18:33], v[126:129], v[166:169], v[18:33]
	v_exp_f32_e32 v218, v34
	v_cvt_pk_bf16_f32 v170, v210, v211
	v_cvt_pk_bf16_f32 v171, v212, v213
	v_cvt_pk_bf16_f32 v172, v214, v215
	v_cvt_pk_bf16_f32 v173, v216, v217
	v_mfma_f32_32x32x16_bf16 v[2:17], v[122:125], v[166:169], v[2:17]
	v_exp_f32_e32 v219, v35
	v_exp_f32_e32 v220, v36
	v_exp_f32_e32 v221, v37
	v_mfma_f32_32x32x16_bf16 v[18:33], v[118:121], v[170:173], v[18:33]
	v_exp_f32_e32 v222, v38
	v_exp_f32_e32 v223, v39
	ds_read_b128 v[194:197], v0
	ds_read_b128 v[150:153], v0 offset:32
	v_mfma_f32_32x32x16_bf16 v[2:17], v[114:117], v[170:173], v[2:17]
	v_exp_f32_e32 v224, v40
	v_exp_f32_e32 v225, v41
	v_cvt_pk_bf16_f32 v166, v218, v219
	v_cvt_pk_bf16_f32 v167, v220, v221
	v_cvt_pk_bf16_f32 v168, v222, v223
	v_cvt_pk_bf16_f32 v169, v224, v225
	ds_read_b128 v[158:161], v0 offset:64
	ds_read_b128 v[162:165], v0 offset:96
	v_mfma_f32_32x32x16_bf16 v[18:33], v[110:113], v[166:169], v[18:33]
	v_exp_f32_e32 v226, v42
	v_exp_f32_e32 v227, v43
	v_exp_f32_e32 v228, v44
	v_mfma_f32_32x32x16_bf16 v[2:17], v[106:109], v[166:169], v[2:17]
	v_exp_f32_e32 v229, v45
	v_exp_f32_e32 v230, v46
	v_exp_f32_e32 v231, v47
	v_exp_f32_e32 v232, v48
	v_exp_f32_e32 v233, v49
	ds_read_b128 v[174:177], v0 offset:128
	ds_read_b128 v[178:181], v0 offset:160
	v_cvt_pk_bf16_f32 v170, v226, v227
	v_cvt_pk_bf16_f32 v171, v228, v229
	v_cvt_pk_bf16_f32 v172, v230, v231
	v_cvt_pk_bf16_f32 v173, v232, v233
	s_nop 1
	v_mfma_f32_32x32x16_bf16 v[18:33], v[102:105], v[170:173], v[18:33]
	v_mfma_f32_32x32x16_bf16 v[2:17], v[98:101], v[170:173], v[2:17]
	s_branch .LBB0_498
.Lmla_fast_rescale:
	v_xor_b32_e32 v149, 32, v187
	v_cmp_lt_i32_e32 vcc, v149, v189
	s_nop 1
	v_cndmask_b32_e32 v149, v187, v149, vcc
	v_lshlrev_b32_e32 v149, 2, v149
	ds_bpermute_b32 v149, v149, v0
	s_waitcnt lgkmcnt(0)
	v_max3_f32 v149, v0, v149, 0
	v_exp_f32_e64 v0, -v149
	v_add_f32_e32 v148, v148, v149
	v_pk_mul_f32 v[32:33], v[32:33], v[0:1] op_sel_hi:[1,0]
	v_pk_mul_f32 v[30:31], v[30:31], v[0:1] op_sel_hi:[1,0]
	v_pk_mul_f32 v[28:29], v[28:29], v[0:1] op_sel_hi:[1,0]
	v_pk_mul_f32 v[26:27], v[26:27], v[0:1] op_sel_hi:[1,0]
	v_pk_mul_f32 v[24:25], v[24:25], v[0:1] op_sel_hi:[1,0]
	v_pk_mul_f32 v[22:23], v[22:23], v[0:1] op_sel_hi:[1,0]
	v_pk_mul_f32 v[20:21], v[20:21], v[0:1] op_sel_hi:[1,0]
	v_pk_mul_f32 v[18:19], v[18:19], v[0:1] op_sel_hi:[1,0]
	v_pk_mul_f32 v[16:17], v[16:17], v[0:1] op_sel_hi:[1,0]
	v_pk_mul_f32 v[14:15], v[14:15], v[0:1] op_sel_hi:[1,0]
	v_pk_mul_f32 v[12:13], v[12:13], v[0:1] op_sel_hi:[1,0]
	v_pk_mul_f32 v[10:11], v[10:11], v[0:1] op_sel_hi:[1,0]
	v_pk_mul_f32 v[8:9], v[8:9], v[0:1] op_sel_hi:[1,0]
	v_pk_mul_f32 v[6:7], v[6:7], v[0:1] op_sel_hi:[1,0]
	v_pk_mul_f32 v[4:5], v[4:5], v[0:1] op_sel_hi:[1,0]
	v_pk_mul_f32 v[2:3], v[2:3], v[0:1] op_sel_hi:[1,0]
	v_mul_f32_e32 v147, v147, v0
	v_sub_f32_e32 v234, v234, v149
	v_sub_f32_e32 v235, v235, v149
	v_sub_f32_e32 v236, v236, v149
	v_sub_f32_e32 v237, v237, v149
	v_sub_f32_e32 v238, v238, v149
	v_sub_f32_e32 v239, v239, v149
	v_sub_f32_e32 v240, v240, v149
	v_sub_f32_e32 v241, v241, v149
	v_sub_f32_e32 v242, v242, v149
	v_sub_f32_e32 v243, v243, v149
	v_sub_f32_e32 v244, v244, v149
	v_sub_f32_e32 v245, v245, v149
	v_sub_f32_e32 v246, v246, v149
	v_sub_f32_e32 v247, v247, v149
	v_sub_f32_e32 v248, v248, v149
	v_sub_f32_e32 v249, v249, v149
	v_sub_f32_e32 v50, v50, v149
	v_sub_f32_e32 v51, v51, v149
	v_sub_f32_e32 v52, v52, v149
	v_sub_f32_e32 v53, v53, v149
	v_sub_f32_e32 v54, v54, v149
	v_sub_f32_e32 v55, v55, v149
	v_sub_f32_e32 v56, v56, v149
	v_sub_f32_e32 v57, v57, v149
	v_sub_f32_e32 v58, v58, v149
	v_sub_f32_e32 v59, v59, v149
	v_sub_f32_e32 v60, v60, v149
	v_sub_f32_e32 v61, v61, v149
	v_sub_f32_e32 v62, v62, v149
	v_sub_f32_e32 v63, v63, v149
	v_sub_f32_e32 v64, v64, v149
	v_sub_f32_e32 v65, v65, v149
	v_sub_f32_e32 v34, v34, v149
	v_sub_f32_e32 v35, v35, v149
	v_sub_f32_e32 v36, v36, v149
	v_sub_f32_e32 v37, v37, v149
	v_sub_f32_e32 v38, v38, v149
	v_sub_f32_e32 v39, v39, v149
	v_sub_f32_e32 v40, v40, v149
	v_sub_f32_e32 v41, v41, v149
	v_sub_f32_e32 v42, v42, v149
	v_sub_f32_e32 v43, v43, v149
	v_sub_f32_e32 v44, v44, v149
	v_sub_f32_e32 v45, v45, v149
	v_sub_f32_e32 v46, v46, v149
	v_sub_f32_e32 v47, v47, v149
	v_sub_f32_e32 v48, v48, v149
	v_sub_f32_e32 v49, v49, v149
	v_exp_f32_e32 v202, v50
	v_exp_f32_e32 v203, v51
	v_exp_f32_e32 v204, v52
	v_exp_f32_e32 v205, v53
	v_exp_f32_e32 v206, v54
	v_exp_f32_e32 v207, v55
	v_exp_f32_e32 v208, v56
	v_exp_f32_e32 v209, v57
	v_exp_f32_e32 v210, v58
	v_exp_f32_e32 v211, v59
	v_exp_f32_e32 v212, v60
	v_exp_f32_e32 v213, v61
	v_exp_f32_e32 v214, v62
	v_exp_f32_e32 v215, v63
	v_exp_f32_e32 v216, v64
	v_exp_f32_e32 v217, v65
	s_branch .Lmla_fast_ok
